# attention sub-step 1: row-sum add chain interleaved into the gaps of the six P.V MFMAs that follow the barrier (was a 17-add tail after the last MFMA)
# baseline (speedup 1.0000x reference)
; __device__ __forceinline__ unsigned pk2(float lo, float hi) { return pg8::cvt_pk_bf16(lo, hi); }
; #define MFMA32(a, b, c) __builtin_amdgcn_mfma_f32_32x32x16_bf16((a), (b), (c), 0, 0, 0)
; __device__ __forceinline__ void attn_phase(const Args& a, int l, bool with_ctx, unsigned char* lds) {
;     ...
;                 float ps = 0.f;
; #pragma unroll
;                 for (int r = 0; r < 16; ++r) { S[r] = __builtin_amdgcn_exp2f(S[r]); ps += S[r]; }
;                 lrun += ps;
;                 u32x4 p0, p1;
;                 p0.x = pk2(S[0], S[1]); p0.y = pk2(S[2], S[3]); p0.z = pk2(S[4], S[5]); p0.w = pk2(S[6], S[7]);
;                 p1.x = pk2(S[8], S[9]); p1.y = pk2(S[10], S[11]); p1.z = pk2(S[12], S[13]); p1.w = pk2(S[14], S[15]);
;                 const bf16x8 pa0 = __builtin_bit_cast(bf16x8, p0), pa1 = __builtin_bit_cast(bf16x8, p1);
; #pragma unroll
;                 for (int j = 0; j < 4; ++j) O[j] = MFMA32(vf[2 * j], pa0, O[j]);
; #pragma unroll
;                 for (int j = 0; j < 4; ++j) O[j] = MFMA32(vf[2 * j + 1], pa1, O[j]);
;             }
;             if (t + 1 < nt) { unsigned char* kd = kdst + (cur ^ 1) * BUF; unsigned char* vd = vdst + (cur ^ 1) * BUF;
;                 *(u32x4*)kd = k0; *(u32x4*)(kd + 9216) = k1; *(u32x4*)vd = v0; *(u32x4*)(vd + 9216) = v1; }
;             __syncthreads();
.LBB0_412:
	v_exp_f32_e32 v67, v68
	v_exp_f32_e32 v68, v69
	v_exp_f32_e32 v69, v70
	v_exp_f32_e32 v70, v71
	v_exp_f32_e32 v71, v72
	v_exp_f32_e32 v72, v73
	v_exp_f32_e32 v73, v74
	v_exp_f32_e32 v74, v75
	v_cvt_pk_bf16_f32 v184, v67, v68
	v_cvt_pk_bf16_f32 v185, v69, v70
	v_cvt_pk_bf16_f32 v186, v71, v72
	v_cvt_pk_bf16_f32 v187, v73, v74
	v_exp_f32_e32 v75, v76
	v_exp_f32_e32 v76, v77
	s_waitcnt lgkmcnt(11)
	v_mfma_f32_32x32x16_bf16 v[50:65], v[136:139], v[184:187], v[50:65]
	v_exp_f32_e32 v77, v78
	v_exp_f32_e32 v78, v79
	v_exp_f32_e32 v79, v80
	v_exp_f32_e32 v80, v81
	v_exp_f32_e32 v81, v82
	v_exp_f32_e32 v82, v83
	v_cvt_pk_bf16_f32 v214, v75, v76
	s_waitcnt lgkmcnt(9)
	v_mfma_f32_32x32x16_bf16 v[34:49], v[140:143], v[184:187], v[34:49]
	v_cvt_pk_bf16_f32 v215, v77, v78
	v_cvt_pk_bf16_f32 v216, v79, v80
	v_cvt_pk_bf16_f32 v217, v81, v82
	s_andn2_b64 vcc, exec, s[10:11]
	s_waitcnt lgkmcnt(0)
	s_barrier
	v_mfma_f32_32x32x16_bf16 v[18:33], v[144:147], v[184:187], v[18:33]
	v_add_f32_e32 v67, 0, v67
	v_add_f32_e32 v67, v68, v67
	v_add_f32_e32 v67, v69, v67
	s_waitcnt lgkmcnt(5)
	v_mfma_f32_32x32x16_bf16 v[2:17], v[132:135], v[184:187], v[2:17]
	v_add_f32_e32 v67, v70, v67
	v_add_f32_e32 v67, v71, v67
	v_add_f32_e32 v67, v72, v67
	v_mfma_f32_32x32x16_bf16 v[50:65], v[116:119], v[214:217], v[50:65]
	v_add_f32_e32 v67, v73, v67
	v_add_f32_e32 v67, v74, v67
	v_add_f32_e32 v67, v75, v67
	v_mfma_f32_32x32x16_bf16 v[34:49], v[120:123], v[214:217], v[34:49]
	v_add_f32_e32 v67, v76, v67
	v_add_f32_e32 v67, v77, v67
	v_add_f32_e32 v67, v78, v67
	v_mfma_f32_32x32x16_bf16 v[18:33], v[124:127], v[214:217], v[18:33]
	v_add_f32_e32 v67, v79, v67
	v_add_f32_e32 v67, v80, v67
	v_add_f32_e32 v67, v81, v67
	s_waitcnt lgkmcnt(4)
	v_mfma_f32_32x32x16_bf16 v[2:17], v[128:131], v[214:217], v[2:17]
	v_add_f32_e32 v67, v82, v67
	v_add_f32_e32 v171, v171, v67
.LBB0_414:
	s_mov_b64 s[10:11], 0x2000
	v_lshl_add_u64 v[172:173], v[172:173], 0, s[10:11]
	s_cmp_eq_u32 s7, s14
	v_lshl_add_u64 v[174:175], v[174:175], 0, s[94:95]
	s_cbranch_scc1 .LBB0_416
	s_mov_b32 s15, s14
	s_branch .LBB0_406
